# GLA chain output waves rewritten: bulk LDS reads + interleaved MFMA chains, outputs staged through LDS and stored as full 128-byte rows one half-step later
# speedup vs baseline: 1.0158x; 1.0128x over previous
; #define LAS __attribute__((address_space(3)))
; __device__ __forceinline__ unsigned pk2(float lo, float hi) { const v2f_t f = {lo, hi}; const v2bf_t b = __builtin_convertvector(f, v2bf_t); return __builtin_bit_cast(unsigned, b); }
; __device__ __forceinline__ int opaque_tid() { int t = threadIdx.x; asm volatile("" : "+v"(t)); return t; }
; __device__ __forceinline__ void gla_chain(const Params& p, LAS unsigned char* lds) {
;     ...
;     const int tid = opaque_tid(), lane = tid & 63, wave = __builtin_amdgcn_readfirstlane(tid >> 6), fr = lane & 15, fq = lane >> 4;
;     const int chain = blockIdx.x & 31, vg = blockIdx.x >> 5, b = chain >> 3, h = (chain >> 1) & 3, dir = chain & 1;
;     unsigned char* C = p.ws + OFF_C;
;     const bf16_t* QTg = (const bf16_t*)(C + C_QT) + (size_t)chain * 68 * 8192; const bf16_t* KHg = (const bf16_t*)(C + C_KHT) + (size_t)chain * 68 * 8192;
;     const bf16_t* Pg = (const bf16_t*)(C + C_P) + (size_t)chain * 68 * 4096; const float* Eg = (const float*)(C + C_E) + (size_t)chain * 68 * 128;
;     const bf16_t* vtl = (const bf16_t*)(C + C_VTL) + ((size_t)b * 1024 + h * 256 + vg * 64 + (tid >> 3)) * T + (tid & 7) * 8;
;     const bf16_t* vtc = (const bf16_t*)(C + C_VTC) + ((size_t)b * 1024 + h * 256 + vg * 64 + (tid >> 3)) * CTXL + (tid & 7) * 8;
;     bf16_t* Og = (bf16_t*)(C + (dir ? C_OB : C_OF)) + h * 256 + vg * 64 + (wave & 3) * 16 + fq * 4;
;     LAS unsigned char* st = lds + CH_ST + (wave & 3) * 4352;
;     u32x4 ra0, ra1, ra2, ra3, ra4, ra5, rb0, rb1, rb2, rb3, rb4, rb5; f32x4 rae = {0.f, 0.f, 0.f, 0.f}, rbe = {0.f, 0.f, 0.f, 0.f};
;     ...
;                 for (int i2 = 0; i2 < 2; ++i2) { u32x2 ow; ow.x = pk2(o[i2][0], o[i2][1]); ow.y = pk2(o[i2][2], o[i2][3]); *(u32x2*)(Og + (size_t)(rb + (ih * 2 + i2) * 16 + fr) * 1024) = ow; }
.LBB0_456:
	v_lshlrev_b64 v[28:29], 13, v[28:29]
	v_lshl_add_u64 v[28:29], s[10:11], 0, v[28:29]
	v_mov_b32_e32 v144, v142
	v_mov_b32_e32 v145, v65
	v_lshl_add_u64 v[28:29], v[28:29], 0, v[144:145]
	s_mov_b64 s[2:3], 0x2141c000
	v_lshl_add_u64 v[146:147], v[28:29], 0, s[2:3]
	v_readlane_b32 s2, v239, 27
	s_add_u32 s2, s10, s2
	s_addc_u32 s3, s11, 0
	v_readlane_b32 s37, v239, 49
	s_add_u32 s2, s2, s37
	s_addc_u32 s3, s3, 0
	v_readlane_b32 s37, v239, 50
	s_add_u32 s2, s2, s37
	s_addc_u32 s3, s3, 0
	s_lshl_b32 s37, s35, 4
	s_and_b32 s37, s37, 48
	s_lshl_b32 s38, s37, 1
	s_add_u32 s2, s2, s38
	s_addc_u32 s3, s3, 0
	v_mov_b32_e32 v33, v65
	v_lshl_add_u64 v[28:29], s[2:3], 0, v[32:33]
	s_mov_b64 s[2:3], 0x134fc000
	v_mov_b32_e32 v31, v65
	v_lshl_add_u64 v[148:149], v[28:29], 0, s[2:3]
	v_lshl_add_u64 v[28:29], v[138:139], 1, s[26:27]
	v_lshl_add_u64 v[152:153], s[28:29], 0, v[30:31]
	v_readlane_b32 s3, v239, 55
	v_readlane_b32 s28, v239, 56
	v_readlane_b32 s29, v239, 57
	v_lshl_add_u64 v[150:151], v[28:29], 0, v[144:145]
	v_or_b32_e32 v28, s37, v154
	s_movk_i32 s2, 0x90
	v_lshlrev_b32_e32 v158, 4, v36
	v_add_u32_e32 v159, s3, v35
	v_add_u32_e32 v32, s28, v35
	v_add_u32_e32 v33, s29, v35
	v_mov_b32_e32 v35, s29
	v_mov_b32_e32 v98, v65
	v_mov_b32_e32 v99, v65
	v_mov_b32_e32 v100, v65
	v_mov_b32_e32 v101, v65
	v_mad_u32_u24 v29, v28, s2, 0
	s_cmp_lt_i32 s35, 4
	v_add_u32_e32 v30, s36, v158
	v_add_u32_e32 v31, 0x2400, v159
	v_mad_u32_u24 v28, v28, s2, v35
	v_mul_u32_u24_e32 v161, 0x90, v154
	v_or_b32_e32 v35, 16, v154
	v_lshlrev_b32_e32 v173, 4, v34
	v_add_u32_e32 v34, s3, v158
	v_mov_b64_e32 v[104:105], v[100:101]
	v_mov_b64_e32 v[94:95], v[98:99]
	v_mov_b64_e32 v[90:91], v[98:99]
	v_mov_b64_e32 v[74:75], v[98:99]
	v_mov_b64_e32 v[66:67], v[98:99]
	v_mov_b64_e32 v[60:61], v[98:99]
	v_mov_b64_e32 v[56:57], v[98:99]
	s_cselect_b64 s[26:27], -1, 0
	v_add_u32_e32 v160, 0, v158
	v_add_u32_e32 v170, s36, v157
	v_mul_u32_u24_e32 v171, 0x110, v35
	v_mul_u32_u24_e32 v172, 0x90, v35
	v_add_u32_e32 v174, s28, v158
	s_mov_b32 s35, 0
	v_add_u32_e32 v175, v29, v158
	v_add_u32_e32 v176, v30, v157
	v_add_u32_e32 v177, v31, v130
	v_add_u32_e32 v178, v32, v130
	v_add_u32_e32 v179, v33, v130
	v_add_u32_e32 v180, v28, v158
	v_add_u32_e32 v181, v34, v161
	v_mov_b64_e32 v[102:103], v[98:99]
	v_mov_b64_e32 v[96:97], v[100:101]
	v_mov_b64_e32 v[92:93], v[100:101]
	v_mov_b64_e32 v[76:77], v[100:101]
	v_mov_b64_e32 v[68:69], v[100:101]
	v_mov_b64_e32 v[62:63], v[100:101]
	v_mov_b64_e32 v[58:59], v[100:101]
	v_bfe_u32 v247, v194, 4, 4
	v_lshlrev_b32_e32 v247, 3, v247
	v_and_b32_e32 v248, 7, v194
	v_lshlrev_b32_e32 v248, 4, v248
	v_bfe_u32 v249, v194, 3, 5
	v_add_u32_e32 v240, v161, v247
	v_add_u32_e32 v240, 0x23410, v240
	v_mul_u32_u24_e32 v241, 0x90, v249
	v_add_u32_e32 v241, v241, v248
	v_add_u32_e32 v241, 0x23410, v241
	v_lshlrev_b32_e32 v249, 11, v249
	v_add_u32_e32 v248, v248, v249
	v_sub_u32_e32 v248, v248, v247
	v_mov_b32_e32 v249, 0
	v_lshl_add_u64 v[244:245], v[148:149], 0, v[248:249]
	s_mov_b32 s98, 0x10000
	s_mov_b32 s99, 0
	s_mov_b32 s100, 0
	s_mov_b32 s101, 0
	s_mov_b32 s37, -2
	s_add_i32 s36, s37, 2
	s_cmpk_gt_u32 s37, 0x41
	s_cselect_b64 s[28:29], -1, 0
	s_add_i32 s38, s37, 4
	s_min_u32 s38, s38, 0x43
	s_cmp_gt_u32 s38, 3
	s_cselect_b32 s2, 0x47, 3
	s_sub_i32 s39, s2, s38
	s_and_b64 s[2:3], s[78:79], exec
	s_cselect_b32 s2, s38, s39
	s_ashr_i32 s3, s2, 31
	s_lshl_b64 s[38:39], s[2:3], 13
	s_lshl_b64 s[40:41], s[2:3], 14
	s_add_u32 s42, s1, s40
	s_addc_u32 s43, s30, s41
	s_add_u32 s40, s31, s40
	s_addc_u32 s41, s34, s41
	s_cmp_lt_i32 s2, 4
	s_waitcnt vmcnt(11)
	v_lshl_add_u64 v[44:45], v[150:151], 0, s[38:39]
	s_cselect_b64 vcc, -1, 0
	s_lshl_b32 s38, s2, 6
	s_ashr_i32 s39, s38, 31
	v_lshl_add_u64 v[46:47], s[38:39], 1, v[132:133]
	s_mov_b32 s39, s73
	v_lshl_add_u64 v[48:49], s[38:39], 1, v[146:147]
	s_movk_i32 s38, 0xfe00
	s_mov_b32 s39, -1
	v_lshl_add_u64 v[28:29], v[134:135], 1, s[42:43]
	v_lshl_add_u64 v[30:31], v[136:137], 1, s[42:43]
	v_lshl_add_u64 v[36:37], v[138:139], 1, s[40:41]
	v_lshl_add_u64 v[38:39], v[140:141], 1, s[40:41]
	v_lshl_add_u64 v[48:49], v[48:49], 0, s[38:39]
	v_lshl_add_u64 v[28:29], v[28:29], 0, v[64:65]
	v_lshl_add_u64 v[32:33], v[30:31], 0, v[64:65]
	v_lshl_add_u64 v[36:37], v[36:37], 0, v[144:145]
	v_lshl_add_u64 v[40:41], v[38:39], 0, v[144:145]
	v_cndmask_b32_e32 v47, v49, v47, vcc
	v_cndmask_b32_e32 v46, v48, v46, vcc
	s_lshl_b64 s[2:3], s[2:3], 9
	global_load_dwordx4 v[28:31], v[28:29], off
	s_nop 0
	global_load_dwordx4 v[32:35], v[32:33], off
	s_nop 0
	global_load_dwordx4 v[36:39], v[36:37], off
	s_nop 0
	global_load_dwordx4 v[40:43], v[40:41], off
	global_load_dwordx4 v[48:51], v[46:47], off
	v_lshl_add_u64 v[46:47], v[152:153], 0, s[2:3]
	global_load_dwordx4 v[52:55], v[44:45], off
	s_nop 0
	global_load_dwordx4 v[44:47], v[46:47], off
	s_mov_b32 s37, 0
	s_waitcnt lgkmcnt(0)
	s_barrier

; #define LAS __attribute__((address_space(3)))
; __device__ __forceinline__ unsigned pk2(float lo, float hi) { const v2f_t f = {lo, hi}; const v2bf_t b = __builtin_convertvector(f, v2bf_t); return __builtin_bit_cast(unsigned, b); }
; __device__ __forceinline__ void gla_chain(const Params& p, LAS unsigned char* lds) {
;     ...
;         if (wave >= 4) {
;             const int mc = dir == 0 ? ci : (ci < 4 ? 3 - ci : 71 - ci);
;             const int rb = mc < 4 ? ROWS_LAT + b * CTXL + mc * 64 : b * T + (mc - 4) * 64;
;             const LAS unsigned char* sti = st + (ci & 1) * (4 * 4352);
;             bf16x8 a_st[4];
; #pragma unroll
;             for (int ks = 0; ks < 4; ++ks) a_st[ks] = *(const LAS bf16x8*)(sti + fr * 272 + ks * 64 + fq * 16);
; #pragma unroll
;             for (int ih = 0; ih < 2; ++ih) {
;                 bf16x8 bq[2][4], bp[2][2]; f32x4 o[2];
; #pragma unroll
;                 for (int i2 = 0; i2 < 2; ++i2) { const int it = ih * 2 + i2; o[i2] = (f32x4){0.f, 0.f, 0.f, 0.f};
; #pragma unroll
;                     for (int ks = 0; ks < 4; ++ks) bq[i2][ks] = *(const LAS bf16x8*)(cur + (it * 16 + fr) * 272 + ks * 64 + fq * 16);
; #pragma unroll
;                     for (int ks = 0; ks < 2; ++ks) bp[i2][ks] = *(const LAS bf16x8*)(cur + CH_P + (it * 16 + fr) * 144 + ks * 64 + fq * 16); }
; #pragma unroll
;                 for (int ks = 0; ks < 4; ++ks)
; #pragma unroll
;                     for (int i2 = 0; i2 < 2; ++i2) o[i2] = __builtin_amdgcn_mfma_f32_16x16x32_bf16(a_st[ks], bq[i2][ks], o[i2], 0, 0, 0);
; #pragma unroll
;                 for (int ks = 0; ks < 2; ++ks)
; #pragma unroll
;                     for (int i2 = 0; i2 < 2; ++i2) o[i2] = __builtin_amdgcn_mfma_f32_16x16x32_bf16(a_v[ks], bp[i2][ks], o[i2], 0, 0, 0);
; #pragma unroll
;                 for (int i2 = 0; i2 < 2; ++i2) { u32x2 ow; ow.x = pk2(o[i2][0], o[i2][1]); ow.y = pk2(o[i2][2], o[i2][3]); *(u32x2*)(Og + (size_t)(rb + (ih * 2 + i2) * 16 + fr) * 1024) = ow; }
;             }
.LBB0_460:
	s_andn2_b64 vcc, exec, s[2:3]
	s_cbranch_vccnz .Lch_mid
	s_waitcnt lgkmcnt(2)
	v_add_u32_e32 v250, v160, v157
	v_add_u32_e32 v251, v160, v171
	v_add_u32_e32 v252, v160, v161
	v_add_u32_e32 v253, v160, v172
	s_cmp_eq_u32 s37, 0
	s_cbranch_scc1 .Lrb_nofl_a
	ds_read_b128 v[208:211], v241 offset:9216
	ds_read_b128 v[212:215], v241 offset:13824
	v_lshl_add_u64 v[246:247], v[244:245], 0, s[100:101]
	v_lshl_add_u64 v[248:249], v[246:247], 0, s[98:99]
.Lrb_nofl_a:
	ds_read_b128 v[56:59], v176
	ds_read_b128 v[74:77], v250
	ds_read_b128 v[90:93], v251
	ds_read_b128 v[60:63], v176 offset:64
	ds_read_b128 v[78:81], v250 offset:64
	ds_read_b128 v[94:97], v251 offset:64
	ds_read_b128 v[66:69], v176 offset:128
	ds_read_b128 v[82:85], v250 offset:128
	ds_read_b128 v[98:101], v251 offset:128
	s_cmp_gt_u32 s37, 3
	s_cselect_b32 s2, 0x47, 3
	s_add_i32 s38, s2, s35
	s_and_b64 s[2:3], s[78:79], exec
	s_cselect_b32 s2, s37, s38
	s_cmp_lt_i32 s2, 4
	s_cselect_b32 s3, 8, 12
	v_readlane_b32 s39, v239, 24
	s_cselect_b32 s38, s33, 0xffffff00
	s_nop 0
	s_lshl_b32 s3, s39, s3
	s_add_i32 s3, s3, s38
	s_lshl_b32 s2, s2, 6
	s_add_i32 s2, s2, s3
	s_waitcnt lgkmcnt(7)
	v_mfma_f32_16x16x32_bf16 v[182:185], v[56:59], v[74:77], 0
	s_cmp_eq_u32 s37, 0
	s_cbranch_scc1 .Lrb_nofl_b
	global_store_dwordx4 v[246:247], v[208:211], off
	global_store_dwordx4 v[248:249], v[212:215], off
.Lrb_nofl_b:
	s_waitcnt lgkmcnt(6)
	v_mfma_f32_16x16x32_bf16 v[186:189], v[56:59], v[90:93], 0
	ds_read_b128 v[70:73], v176 offset:192
	ds_read_b128 v[86:89], v250 offset:192
	ds_read_b128 v[102:105], v251 offset:192
	ds_read_b128 v[74:77], v251 offset:4352
	ds_read_b128 v[90:93], v251 offset:8704
	s_waitcnt lgkmcnt(9)
	v_mfma_f32_16x16x32_bf16 v[182:185], v[60:63], v[78:81], v[182:185]
	s_waitcnt lgkmcnt(8)
	v_mfma_f32_16x16x32_bf16 v[186:189], v[60:63], v[94:97], v[186:189]
	ds_read_b128 v[106:109], v252 offset:35840
	ds_read_b128 v[110:113], v252 offset:35904
	ds_read_b128 v[114:117], v253 offset:35840
	ds_read_b128 v[118:121], v253 offset:35904
	ds_read_b128 v[78:81], v251 offset:4416
	ds_read_b128 v[94:97], v251 offset:8768
	s_waitcnt lgkmcnt(12)
	v_mfma_f32_16x16x32_bf16 v[182:185], v[66:69], v[82:85], v[182:185]
	s_waitcnt lgkmcnt(11)
	v_mfma_f32_16x16x32_bf16 v[186:189], v[66:69], v[98:101], v[186:189]
	ds_read_b128 v[82:85], v251 offset:4480
	ds_read_b128 v[98:101], v251 offset:8832
	s_waitcnt lgkmcnt(11)
	v_mfma_f32_16x16x32_bf16 v[182:185], v[70:73], v[86:89], v[182:185]
	s_waitcnt lgkmcnt(10)
	v_mfma_f32_16x16x32_bf16 v[186:189], v[70:73], v[102:105], v[186:189]
	ds_read_b128 v[86:89], v251 offset:4544
	ds_read_b128 v[102:105], v251 offset:8896
	s_waitcnt lgkmcnt(9)
	v_mfma_f32_16x16x32_bf16 v[182:185], v[126:129], v[106:109], v[182:185]
	s_waitcnt lgkmcnt(7)
	v_mfma_f32_16x16x32_bf16 v[186:189], v[126:129], v[114:117], v[186:189]
	ds_read_b128 v[106:109], v253 offset:38144
	ds_read_b128 v[114:117], v253 offset:40448
	v_mfma_f32_16x16x32_bf16 v[182:185], v[122:125], v[110:113], v[182:185]
	s_waitcnt lgkmcnt(8)
	v_mfma_f32_16x16x32_bf16 v[186:189], v[122:125], v[118:121], v[186:189]
	ds_read_b128 v[110:113], v253 offset:38208
	ds_read_b128 v[118:121], v253 offset:40512
	v_mfma_f32_16x16x32_bf16 v[190:193], v[56:59], v[74:77], 0
	v_mfma_f32_16x16x32_bf16 v[204:207], v[56:59], v[90:93], 0
	s_waitcnt lgkmcnt(9)
	v_mfma_f32_16x16x32_bf16 v[190:193], v[60:63], v[78:81], v[190:193]
	s_waitcnt lgkmcnt(8)
	v_mfma_f32_16x16x32_bf16 v[204:207], v[60:63], v[94:97], v[204:207]
	s_waitcnt lgkmcnt(7)
	v_mfma_f32_16x16x32_bf16 v[190:193], v[66:69], v[82:85], v[190:193]
	s_waitcnt lgkmcnt(6)
	v_mfma_f32_16x16x32_bf16 v[204:207], v[66:69], v[98:101], v[204:207]
	s_waitcnt lgkmcnt(5)
	v_mfma_f32_16x16x32_bf16 v[190:193], v[70:73], v[86:89], v[190:193]
	s_waitcnt lgkmcnt(4)
	v_mfma_f32_16x16x32_bf16 v[204:207], v[70:73], v[102:105], v[204:207]
	s_waitcnt lgkmcnt(3)
	v_mfma_f32_16x16x32_bf16 v[190:193], v[126:129], v[106:109], v[190:193]
	s_waitcnt lgkmcnt(2)
	v_mfma_f32_16x16x32_bf16 v[204:207], v[126:129], v[114:117], v[204:207]
	s_waitcnt lgkmcnt(1)
	v_mfma_f32_16x16x32_bf16 v[190:193], v[122:125], v[110:113], v[190:193]
	s_waitcnt lgkmcnt(0)
	v_mfma_f32_16x16x32_bf16 v[204:207], v[122:125], v[118:121], v[204:207]
	v_cvt_pk_bf16_f32 v216, v182, v183
	v_cvt_pk_bf16_f32 v217, v184, v185
	v_cvt_pk_bf16_f32 v218, v186, v187
	v_cvt_pk_bf16_f32 v219, v188, v189
	ds_write_b64 v240, v[216:217] offset:0
	ds_write_b64 v240, v[218:219] offset:2304
	s_lshl_b32 s100, s2, 11
	s_nop 4
	v_cvt_pk_bf16_f32 v220, v190, v191
	v_cvt_pk_bf16_f32 v221, v192, v193
	v_cvt_pk_bf16_f32 v222, v204, v205
	v_cvt_pk_bf16_f32 v223, v206, v207
	ds_write_b64 v240, v[220:221] offset:4608
	ds_write_b64 v240, v[222:223] offset:6912

; #define LAS __attribute__((address_space(3)))
; __device__ __forceinline__ unsigned pk2(float lo, float hi) { const v2f_t f = {lo, hi}; const v2bf_t b = __builtin_convertvector(f, v2bf_t); return __builtin_bit_cast(unsigned, b); }
; #define CH_ISSUE(ci, set) CH_ISSUE_X(ci, set)
; #define CH_WRITE(buf, set) CH_WRITE_X(buf, set)
; __device__ __forceinline__ void gla_chain(const Params& p, LAS unsigned char* lds) {
;     ...
;         if (wave >= 4) {
;             const int mc = dir == 0 ? ci : (ci < 4 ? 3 - ci : 71 - ci);
;             const int rb = mc < 4 ? ROWS_LAT + b * CTXL + mc * 64 : b * T + (mc - 4) * 64;
;             const LAS unsigned char* sti = st + (ci & 1) * (4 * 4352);
;             bf16x8 a_st[4];
; #pragma unroll
;             for (int ks = 0; ks < 4; ++ks) a_st[ks] = *(const LAS bf16x8*)(sti + fr * 272 + ks * 64 + fq * 16);
; #pragma unroll
;             for (int ih = 0; ih < 2; ++ih) {
;                 bf16x8 bq[2][4], bp[2][2]; f32x4 o[2];
; #pragma unroll
;                 for (int i2 = 0; i2 < 2; ++i2) { const int it = ih * 2 + i2; o[i2] = (f32x4){0.f, 0.f, 0.f, 0.f};
; #pragma unroll
;                     for (int ks = 0; ks < 4; ++ks) bq[i2][ks] = *(const LAS bf16x8*)(cur + (it * 16 + fr) * 272 + ks * 64 + fq * 16);
; #pragma unroll
;                     for (int ks = 0; ks < 2; ++ks) bp[i2][ks] = *(const LAS bf16x8*)(cur + CH_P + (it * 16 + fr) * 144 + ks * 64 + fq * 16); }
; #pragma unroll
;                 for (int ks = 0; ks < 4; ++ks)
; #pragma unroll
;                     for (int i2 = 0; i2 < 2; ++i2) o[i2] = __builtin_amdgcn_mfma_f32_16x16x32_bf16(a_st[ks], bq[i2][ks], o[i2], 0, 0, 0);
; #pragma unroll
;                 for (int ks = 0; ks < 2; ++ks)
; #pragma unroll
;                     for (int i2 = 0; i2 < 2; ++i2) o[i2] = __builtin_amdgcn_mfma_f32_16x16x32_bf16(a_v[ks], bp[i2][ks], o[i2], 0, 0, 0);
; #pragma unroll
;                 for (int i2 = 0; i2 < 2; ++i2) { u32x2 ow; ow.x = pk2(o[i2][0], o[i2][1]); ow.y = pk2(o[i2][2], o[i2][3]); *(u32x2*)(Og + (size_t)(rb + (ih * 2 + i2) * 16 + fr) * 1024) = ow; }
;             }
;     ...
;     for (int ci = 0; ci < 68; ci += 2) {
;         CH_ISSUE(ci + 2, SET_A);
;         step(ci, lds);
;         CH_WRITE(1, SET_B);
;         __syncthreads();
;         CH_ISSUE(ci + 3, SET_B);
;         step(ci + 1, lds + CH_BUF);
;         CH_WRITE(0, SET_A);
;         __syncthreads();
;     }
.LBB0_466:
	s_andn2_b64 vcc, exec, s[2:3]
	s_cbranch_vccnz .LBB0_457
	s_waitcnt lgkmcnt(2)
	v_add_u32_e32 v254, v170, v158
	v_add_u32_e32 v250, v160, v157
	v_add_u32_e32 v251, v160, v171
	v_add_u32_e32 v252, v174, v161
	v_add_u32_e32 v253, v174, v172
	ds_read_b128 v[208:211], v241 offset:0
	ds_read_b128 v[212:215], v241 offset:4608
	v_lshl_add_u64 v[246:247], v[244:245], 0, s[100:101]
	v_lshl_add_u64 v[248:249], v[246:247], 0, s[98:99]
	ds_read_b128 v[56:59], v254 offset:17408
	ds_read_b128 v[74:77], v250 offset:54784
	ds_read_b128 v[90:93], v251 offset:54784
	ds_read_b128 v[60:63], v254 offset:17472
	ds_read_b128 v[78:81], v250 offset:54848
	ds_read_b128 v[94:97], v251 offset:54848
	ds_read_b128 v[66:69], v254 offset:17536
	ds_read_b128 v[82:85], v250 offset:54912
	ds_read_b128 v[98:101], v251 offset:54912
	s_add_i32 s38, s37, 1
	s_cmp_gt_u32 s37, 3
	s_cselect_b32 s2, 0x47, 3
	s_add_i32 s2, s2, s35
	s_add_i32 s37, s2, -1
	s_and_b64 s[2:3], s[78:79], exec
	s_cselect_b32 s2, s38, s37
	s_cmp_lt_i32 s2, 4
	s_cselect_b32 s3, 8, 12
	v_readlane_b32 s38, v239, 24
	s_cselect_b32 s37, s33, 0xffffff00
	s_nop 0
	s_lshl_b32 s3, s38, s3
	s_add_i32 s3, s3, s37
	s_lshl_b32 s2, s2, 6
	s_add_i32 s2, s2, s3
	s_waitcnt lgkmcnt(7)
	v_mfma_f32_16x16x32_bf16 v[182:185], v[56:59], v[74:77], 0
	global_store_dwordx4 v[246:247], v[208:211], off
	global_store_dwordx4 v[248:249], v[212:215], off
	s_waitcnt lgkmcnt(6)
	v_mfma_f32_16x16x32_bf16 v[186:189], v[56:59], v[90:93], 0
	ds_read_b128 v[70:73], v254 offset:17600
	ds_read_b128 v[86:89], v250 offset:54976
	ds_read_b128 v[102:105], v251 offset:54976
	ds_read_b128 v[74:77], v251 offset:59136
	ds_read_b128 v[90:93], v251 offset:63488
	s_waitcnt lgkmcnt(9)
	v_mfma_f32_16x16x32_bf16 v[182:185], v[60:63], v[78:81], v[182:185]
	s_waitcnt lgkmcnt(8)
	v_mfma_f32_16x16x32_bf16 v[186:189], v[60:63], v[94:97], v[186:189]
	ds_read_b128 v[106:109], v252
	ds_read_b128 v[110:113], v252 offset:64
	ds_read_b128 v[114:117], v253
	ds_read_b128 v[118:121], v253 offset:64
	ds_read_b128 v[78:81], v251 offset:59200
	ds_read_b128 v[94:97], v251 offset:63552
	s_waitcnt lgkmcnt(12)
	v_mfma_f32_16x16x32_bf16 v[182:185], v[66:69], v[82:85], v[182:185]
	s_waitcnt lgkmcnt(11)
	v_mfma_f32_16x16x32_bf16 v[186:189], v[66:69], v[98:101], v[186:189]
	ds_read_b128 v[82:85], v251 offset:59264
	ds_read_b128 v[98:101], v251 offset:63616
	s_waitcnt lgkmcnt(11)
	v_mfma_f32_16x16x32_bf16 v[182:185], v[70:73], v[86:89], v[182:185]
	s_waitcnt lgkmcnt(10)
	v_mfma_f32_16x16x32_bf16 v[186:189], v[70:73], v[102:105], v[186:189]
	ds_read_b128 v[86:89], v251 offset:59328
	ds_read_b128 v[102:105], v251 offset:63680
	s_waitcnt lgkmcnt(9)
	v_mfma_f32_16x16x32_bf16 v[182:185], v[126:129], v[106:109], v[182:185]
	s_waitcnt lgkmcnt(7)
	v_mfma_f32_16x16x32_bf16 v[186:189], v[126:129], v[114:117], v[186:189]
	ds_read_b128 v[106:109], v253 offset:2304
	ds_read_b128 v[114:117], v253 offset:4608
	v_mfma_f32_16x16x32_bf16 v[182:185], v[122:125], v[110:113], v[182:185]
	s_waitcnt lgkmcnt(8)
	v_mfma_f32_16x16x32_bf16 v[186:189], v[122:125], v[118:121], v[186:189]
	ds_read_b128 v[110:113], v253 offset:2368
	ds_read_b128 v[118:121], v253 offset:4672
	v_mfma_f32_16x16x32_bf16 v[190:193], v[56:59], v[74:77], 0
	v_mfma_f32_16x16x32_bf16 v[204:207], v[56:59], v[90:93], 0
	s_waitcnt lgkmcnt(9)
	v_mfma_f32_16x16x32_bf16 v[190:193], v[60:63], v[78:81], v[190:193]
	s_waitcnt lgkmcnt(8)
	v_mfma_f32_16x16x32_bf16 v[204:207], v[60:63], v[94:97], v[204:207]
	s_waitcnt lgkmcnt(7)
	v_mfma_f32_16x16x32_bf16 v[190:193], v[66:69], v[82:85], v[190:193]
	s_waitcnt lgkmcnt(6)
	v_mfma_f32_16x16x32_bf16 v[204:207], v[66:69], v[98:101], v[204:207]
	s_waitcnt lgkmcnt(5)
	v_mfma_f32_16x16x32_bf16 v[190:193], v[70:73], v[86:89], v[190:193]
	s_waitcnt lgkmcnt(4)
	v_mfma_f32_16x16x32_bf16 v[204:207], v[70:73], v[102:105], v[204:207]
	s_waitcnt lgkmcnt(3)
	v_mfma_f32_16x16x32_bf16 v[190:193], v[126:129], v[106:109], v[190:193]
	s_waitcnt lgkmcnt(2)
	v_mfma_f32_16x16x32_bf16 v[204:207], v[126:129], v[114:117], v[204:207]
	s_waitcnt lgkmcnt(1)
	v_mfma_f32_16x16x32_bf16 v[190:193], v[122:125], v[110:113], v[190:193]
	s_waitcnt lgkmcnt(0)
	v_mfma_f32_16x16x32_bf16 v[204:207], v[122:125], v[118:121], v[204:207]
	v_cvt_pk_bf16_f32 v216, v182, v183
	v_cvt_pk_bf16_f32 v217, v184, v185
	v_cvt_pk_bf16_f32 v218, v186, v187
	v_cvt_pk_bf16_f32 v219, v188, v189
	ds_write_b64 v240, v[216:217] offset:9216
	ds_write_b64 v240, v[218:219] offset:11520
	s_lshl_b32 s100, s2, 11
	s_nop 4
	v_cvt_pk_bf16_f32 v220, v190, v191
	v_cvt_pk_bf16_f32 v221, v192, v193
	v_cvt_pk_bf16_f32 v222, v204, v205
	v_cvt_pk_bf16_f32 v223, v206, v207
	ds_write_b64 v240, v[220:221] offset:13824
	ds_write_b64 v240, v[222:223] offset:16128
.LBB0_457:
	s_add_i32 s35, s35, -2
	s_andn2_b64 vcc, exec, s[28:29]
	s_mov_b32 s37, s36
	s_waitcnt lgkmcnt(0)
	s_barrier
	s_cbranch_vccnz .LBB0_458
	s_waitcnt vmcnt(0)
	s_and_b64 vcc, exec, s[26:27]
	s_cbranch_vccnz .Lrb_exit
	ds_read_b128 v[208:211], v241 offset:9216
	ds_read_b128 v[212:215], v241 offset:13824
	v_lshl_add_u64 v[246:247], v[244:245], 0, s[100:101]
	v_lshl_add_u64 v[248:249], v[246:247], 0, s[98:99]
	s_waitcnt lgkmcnt(0)
	global_store_dwordx4 v[246:247], v[208:211], off
	global_store_dwordx4 v[248:249], v[212:215], off
.Lrb_exit:
.LBB0_470:
	v_readlane_b32 s2, v239, 32
	v_readlane_b32 s3, v239, 33
	s_andn2_b64 vcc, exec, s[2:3]
	s_cbranch_vccnz .LBB0_541
	v_readlane_b32 s2, v239, 34
	v_readlane_b32 s3, v239, 35
	s_andn2_b64 vcc, exec, s[2:3]
	s_cbranch_vccnz .LBB0_504
	v_readlane_b32 s1, v239, 37
	s_waitcnt vmcnt(4)
	v_mov_b32_e32 v9, v194
	s_movk_i32 s2, 0x100
	s_ashr_i32 s3, s2, 31
	s_lshr_b32 s3, s3, 26
	s_add_i32 s2, s2, s3
	s_ashr_i32 s49, s2, 6
	s_ashr_i32 s50, s1, 31
	v_readfirstlane_b32 s48, v9
	s_mov_b32 s63, 0
	s_cmp_gt_i32 s1, 31
	s_mov_b32 s28, 0
	s_mov_b32 s26, 0
	s_cbranch_scc1 .LBB0_478
	s_lshr_b32 s2, s50, 29
	s_add_i32 s8, s1, s2
	s_and_b32 s2, s8, -8
	s_sub_i32 s9, s1, s2
	s_cmp_gt_i32 s9, -1
	s_mov_b64 s[2:3], -1
	s_cbranch_scc0 .LBB0_475
	s_lshl_b32 s26, s9, 2
	s_mov_b64 s[2:3], 0

; __global__ void __launch_bounds__(512, 2) mega(Params p_unused) {
;     extern __shared__ __attribute__((aligned(16))) unsigned char shm[];
	.amdhsa_kernel _Z4mega6Params
		.amdhsa_group_segment_fixed_size 18432
		.amdhsa_private_segment_fixed_size 0
		.amdhsa_kernarg_size 440
		.amdhsa_user_sgpr_count 2
		.amdhsa_user_sgpr_dispatch_ptr 0
		.amdhsa_user_sgpr_queue_ptr 0
		.amdhsa_user_sgpr_kernarg_segment_ptr 1
		.amdhsa_user_sgpr_dispatch_id 0
		.amdhsa_user_sgpr_kernarg_preload_length 0
		.amdhsa_user_sgpr_kernarg_preload_offset 0
		.amdhsa_user_sgpr_private_segment_size 0
		.amdhsa_uses_dynamic_stack 0
		.amdhsa_enable_private_segment 0
		.amdhsa_system_sgpr_workgroup_id_x 1
		.amdhsa_system_sgpr_workgroup_id_y 0
		.amdhsa_system_sgpr_workgroup_id_z 0
		.amdhsa_system_sgpr_workgroup_info 0
		.amdhsa_system_vgpr_workitem_id 2
		.amdhsa_next_free_vgpr 256
		.amdhsa_next_free_sgpr 102
		.amdhsa_accum_offset 256
		.amdhsa_reserve_vcc 1
		.amdhsa_float_round_mode_32 0
		.amdhsa_float_round_mode_16_64 0
		.amdhsa_float_denorm_mode_32 3
		.amdhsa_float_denorm_mode_16_64 3
		.amdhsa_dx10_clamp 1
		.amdhsa_ieee_mode 1
		.amdhsa_fp16_overflow 0
		.amdhsa_tg_split 0
		.amdhsa_exception_fp_ieee_invalid_op 0
		.amdhsa_exception_fp_denorm_src 0
		.amdhsa_exception_fp_ieee_div_zero 0
		.amdhsa_exception_fp_ieee_overflow 0
		.amdhsa_exception_fp_ieee_underflow 0
		.amdhsa_exception_fp_ieee_inexact 0
		.amdhsa_exception_int_div_zero 0
	.end_amdhsa_kernel

; __global__ void __launch_bounds__(512, 2) mega(Params p_unused) {
;     extern __shared__ __attribute__((aligned(16))) unsigned char shm[];
amdhsa.kernels:
  - .agpr_count:     0
    .args:
      - .offset:         0
        .size:           184
        .value_kind:     by_value
      - .offset:         184
        .size:           4
        .value_kind:     hidden_block_count_x
      - .offset:         188
        .size:           4
        .value_kind:     hidden_block_count_y
      - .offset:         192
        .size:           4
        .value_kind:     hidden_block_count_z
      - .offset:         196
        .size:           2
        .value_kind:     hidden_group_size_x
      - .offset:         198
        .size:           2
        .value_kind:     hidden_group_size_y
      - .offset:         200
        .size:           2
        .value_kind:     hidden_group_size_z
      - .offset:         202
        .size:           2
        .value_kind:     hidden_remainder_x
      - .offset:         204
        .size:           2
        .value_kind:     hidden_remainder_y
      - .offset:         206
        .size:           2
        .value_kind:     hidden_remainder_z
      - .offset:         224
        .size:           8
        .value_kind:     hidden_global_offset_x
      - .offset:         232
        .size:           8
        .value_kind:     hidden_global_offset_y
      - .offset:         240
        .size:           8
        .value_kind:     hidden_global_offset_z
      - .offset:         248
        .size:           2
        .value_kind:     hidden_grid_dims
      - .offset:         272
        .size:           8
        .value_kind:     hidden_multigrid_sync_arg
      - .offset:         304
        .size:           4
        .value_kind:     hidden_dynamic_lds_size
    .group_segment_fixed_size: 18432
    .kernarg_segment_align: 8
    .kernarg_segment_size: 440
    .language:       OpenCL C
    .language_version:
      - 2
      - 0
    .max_flat_workgroup_size: 512
    .name:           _Z4mega6Params
    .private_segment_fixed_size: 0
    .sgpr_count:     108
    .sgpr_spill_count: 90
    .symbol:         _Z4mega6Params.kd
    .uniform_work_group_size: 1
    .uses_dynamic_stack: false
    .vgpr_count:     256
    .vgpr_spill_count: 0
    .wavefront_size: 64
